# GEMM3 K-loop: LDS-DMA loads use SGPR base + 32-bit VGPR offset (no per-load 64-bit VALU address adds)
# speedup vs baseline: 1.0065x; 1.0023x over previous
; #define PG8_STAGE(bufoff, gbase, voff) do { _Pragma("unroll") for (int _i = 0; _i < 2; ++_i) \
;         __builtin_amdgcn_global_load_lds((const unsigned*)((const char*)(gbase) + (voff)[_i]), (PG8_LAS unsigned*)(lds + (bufoff) + ldsw + _i * 8192), 16, 0, 0); } while (0)
; #define PG8_LDA(dst, b, h) do { _Pragma("unroll") for (int m = 0; m < 4; ++m) _Pragma("unroll") for (int k = 0; k < 2; ++k) dst[m][k] = *(const PG8_LAS bf16x8*)(lds + PG8_SA(b, h) + aoff + m * 2048 + k * 1024); } while (0)
; #define PG8_LDB(dst, b, h) do { _Pragma("unroll") for (int n = 0; n < 2; ++n) _Pragma("unroll") for (int k = 0; k < 2; ++k) dst[n][k] = *(const PG8_LAS bf16x8*)(lds + PG8_SB(b, h) + boff + n * 2048 + k * 1024); } while (0)
; #define PG8_MMA(ai, bj, At, Bt) do { __builtin_amdgcn_s_setprio(1); _Pragma("unroll") for (int m = 0; m < 4; ++m) _Pragma("unroll") for (int n = 0; n < 2; ++n) _Pragma("unroll") for (int k = 0; k < 2; ++k) \
;         acc[ai][bj][m][n] = __builtin_amdgcn_mfma_f32_16x16x32_bf16(Bt[n][k], At[m][k], acc[ai][bj][m][n], 0, 0, 0); __builtin_amdgcn_s_setprio(0); } while (0)
; #define PG8_WAIT_V(n) asm volatile("s_waitcnt vmcnt(" #n ")" ::: "memory")
; #define PG8_WAIT_L(n) asm volatile("s_waitcnt lgkmcnt(" #n ")" ::: "memory")
; #define PG8_BAR __builtin_amdgcn_s_barrier()
; #define PG8_SCHED __builtin_amdgcn_sched_barrier(0)
; template <class Epi, class Sched, bool ALIGN_EPI = false, bool SP2 = false>
; __device__ __forceinline__ void gemm_phase(PG8_LAS unsigned char* lds, const Gemm g, const Sched& S, const Epi& E) {
;     ...
;             if constexpr (SP2) {
;             PG8_LDB(B0, 0, 0); PG8_LDB(B1, 0, 1); PG8_SCHED; PG8_LDA(At, 0, 0); PG8_STAGE(PG8_SA(1, 1), a1 + hstep, voffA);
;             PG8_WAIT_V(8); PG8_WAIT_L(0); PG8_BAR; PG8_MMA(0, 0, At, B0); PG8_MMA(0, 1, At, B1); PG8_BAR; PG8_SCHED;
;             PG8_LDA(At, 0, 1); PG8_STAGE(PG8_SB(0, 0), b2, voffB); PG8_STAGE(PG8_SB(0, 1), b2 + hstep, voffB); PG8_STAGE(PG8_SA(0, 0), a2, voffA);
;             PG8_WAIT_V(8); PG8_WAIT_L(0); PG8_BAR; PG8_MMA(1, 0, At, B0); PG8_MMA(1, 1, At, B1); PG8_BAR; PG8_SCHED;
.LBB0_2650:
	ds_read_b128 v[10:13], v195
	ds_read_b128 v[14:17], v195 offset:1024
	ds_read_b128 v[42:45], v195 offset:2048
	ds_read_b128 v[46:49], v195 offset:3072
	ds_read_b128 v[50:53], v238
	ds_read_b128 v[54:57], v238 offset:1024
	ds_read_b128 v[58:61], v238 offset:2048
	ds_read_b128 v[62:65], v238 offset:3072
	s_add_u32 s88, s86, 0xfff00080
	s_addc_u32 s89, s87, -1
	s_cmp_eq_u32 s93, 60
	s_cselect_b32 s91, s19, s89
	s_cselect_b32 s90, s69, s88
	s_cselect_b32 s89, s77, s92
	s_cselect_b32 s88, s79, s85
	s_add_i32 m0, s62, 0xc000
	ds_read_b128 v[66:69], v239
	ds_read_b128 v[70:73], v239 offset:1024
	ds_read_b128 v[170:173], v239 offset:2048
	ds_read_b128 v[174:177], v239 offset:3072
	ds_read_b128 v[178:181], v239 offset:4096
	ds_read_b128 v[208:211], v239 offset:5120
	ds_read_b128 v[212:215], v239 offset:6144
	ds_read_b128 v[216:219], v239 offset:7168
	global_load_lds_dwordx4 v200, s[86:87]
	s_add_i32 m0, s62, 0xe000
	s_nop 0
	global_load_lds_dwordx4 v202, s[86:87]
	s_waitcnt vmcnt(8)
	s_waitcnt lgkmcnt(0)
	s_barrier
	s_setprio 1
	s_waitcnt lgkmcnt(0)
	v_mfma_f32_16x16x32_bf16 v[6:9], v[10:13], v[66:69], v[6:9]
	v_mfma_f32_16x16x32_bf16 v[2:5], v[42:45], v[66:69], v[2:5]
	v_mfma_f32_16x16x32_bf16 v[158:161], v[10:13], v[170:173], v[158:161]
	v_mfma_f32_16x16x32_bf16 v[154:157], v[42:45], v[170:173], v[154:157]
	v_mfma_f32_16x16x32_bf16 v[142:145], v[10:13], v[178:181], v[142:145]
	v_mfma_f32_16x16x32_bf16 v[138:141], v[42:45], v[178:181], v[138:141]
	v_mfma_f32_16x16x32_bf16 v[126:129], v[10:13], v[212:215], v[126:129]
	v_mfma_f32_16x16x32_bf16 v[122:125], v[42:45], v[212:215], v[122:125]
	v_mfma_f32_16x16x32_bf16 v[6:9], v[14:17], v[70:73], v[6:9]
	v_mfma_f32_16x16x32_bf16 v[2:5], v[46:49], v[70:73], v[2:5]
	v_mfma_f32_16x16x32_bf16 v[158:161], v[14:17], v[174:177], v[158:161]
	v_mfma_f32_16x16x32_bf16 v[154:157], v[46:49], v[174:177], v[154:157]
	v_mfma_f32_16x16x32_bf16 v[142:145], v[14:17], v[208:211], v[142:145]
	v_mfma_f32_16x16x32_bf16 v[138:141], v[46:49], v[208:211], v[138:141]
	v_mfma_f32_16x16x32_bf16 v[126:129], v[14:17], v[216:219], v[126:129]
	v_mfma_f32_16x16x32_bf16 v[122:125], v[46:49], v[216:219], v[122:125]
	s_setprio 0
	s_setprio 1
	v_mfma_f32_16x16x32_bf16 v[166:169], v[50:53], v[66:69], v[166:169]
	v_mfma_f32_16x16x32_bf16 v[66:69], v[58:61], v[66:69], v[162:165]
	v_mfma_f32_16x16x32_bf16 v[146:149], v[58:61], v[170:173], v[146:149]
	v_mfma_f32_16x16x32_bf16 v[134:137], v[50:53], v[178:181], v[134:137]
	v_mfma_f32_16x16x32_bf16 v[130:133], v[58:61], v[178:181], v[130:133]
	v_mfma_f32_16x16x32_bf16 v[118:121], v[50:53], v[212:215], v[118:121]
	v_mfma_f32_16x16x32_bf16 v[114:117], v[58:61], v[212:215], v[114:117]
	v_mfma_f32_16x16x32_bf16 v[166:169], v[54:57], v[70:73], v[166:169]
	v_mfma_f32_16x16x32_bf16 v[66:69], v[62:65], v[70:73], v[66:69]
	v_mfma_f32_16x16x32_bf16 v[70:73], v[50:53], v[170:173], v[150:153]
	v_mfma_f32_16x16x32_bf16 v[146:149], v[62:65], v[174:177], v[146:149]
	v_mfma_f32_16x16x32_bf16 v[134:137], v[54:57], v[208:211], v[134:137]
	v_mfma_f32_16x16x32_bf16 v[130:133], v[62:65], v[208:211], v[130:133]
	v_mfma_f32_16x16x32_bf16 v[118:121], v[54:57], v[216:219], v[118:121]
	v_mfma_f32_16x16x32_bf16 v[114:117], v[62:65], v[216:219], v[114:117]
	v_mfma_f32_16x16x32_bf16 v[70:73], v[54:57], v[174:177], v[70:73]
	s_setprio 0
	s_barrier
	s_add_i32 vcc_lo, s96, s61
	s_mov_b32 m0, vcc_lo
	ds_read_b128 v[150:153], v239 offset:16384
	ds_read_b128 v[162:165], v239 offset:17408
	ds_read_b128 v[170:173], v239 offset:18432
	ds_read_b128 v[174:177], v239 offset:19456
	ds_read_b128 v[178:181], v239 offset:20480
	ds_read_b128 v[208:211], v239 offset:21504
	ds_read_b128 v[212:215], v239 offset:22528
	ds_read_b128 v[216:219], v239 offset:23552
	global_load_lds_dwordx4 v186, s[88:89]
	s_add_i32 m0, vcc_lo, 0x2000
	s_add_u32 vcc_lo, s88, 0x100000
	s_addc_u32 vcc_hi, s89, 0
	s_add_i32 s58, s70, s61
	global_load_lds_dwordx4 v190, s[88:89]
	s_mov_b32 m0, s58
	s_nop 0
	global_load_lds_dwordx4 v186, vcc
	s_add_i32 m0, s58, 0x2000
	s_nop 0
	global_load_lds_dwordx4 v190, vcc
	s_mov_b32 m0, s62
	s_nop 0
	global_load_lds_dwordx4 v184, s[90:91]
	s_mov_b32 m0, s63
	s_nop 0
	global_load_lds_dwordx4 v188, s[90:91]
	s_waitcnt vmcnt(8)
	s_waitcnt lgkmcnt(0)
	s_barrier
	s_setprio 1
	s_waitcnt lgkmcnt(0)
	v_mfma_f32_16x16x32_bf16 v[110:113], v[10:13], v[150:153], v[110:113]
	v_mfma_f32_16x16x32_bf16 v[106:109], v[42:45], v[150:153], v[106:109]
	v_mfma_f32_16x16x32_bf16 v[94:97], v[10:13], v[170:173], v[94:97]
	v_mfma_f32_16x16x32_bf16 v[90:93], v[42:45], v[170:173], v[90:93]
	v_mfma_f32_16x16x32_bf16 v[78:81], v[10:13], v[178:181], v[78:81]
	v_mfma_f32_16x16x32_bf16 v[74:77], v[42:45], v[178:181], v[74:77]
	v_mfma_f32_16x16x32_bf16 v[10:13], v[10:13], v[212:215], v[30:33]
	v_mfma_f32_16x16x32_bf16 v[110:113], v[14:17], v[162:165], v[110:113]
	v_mfma_f32_16x16x32_bf16 v[106:109], v[46:49], v[162:165], v[106:109]
	v_mfma_f32_16x16x32_bf16 v[94:97], v[14:17], v[174:177], v[94:97]
	v_mfma_f32_16x16x32_bf16 v[90:93], v[46:49], v[174:177], v[90:93]
	v_mfma_f32_16x16x32_bf16 v[78:81], v[14:17], v[208:211], v[78:81]
	v_mfma_f32_16x16x32_bf16 v[74:77], v[46:49], v[208:211], v[74:77]
	v_mfma_f32_16x16x32_bf16 v[10:13], v[14:17], v[216:219], v[10:13]
	v_mfma_f32_16x16x32_bf16 v[14:17], v[42:45], v[212:215], v[26:29]
	v_mfma_f32_16x16x32_bf16 v[14:17], v[46:49], v[216:219], v[14:17]
	s_setprio 0
	s_setprio 1
	v_mfma_f32_16x16x32_bf16 v[26:29], v[50:53], v[150:153], v[102:105]
	v_mfma_f32_16x16x32_bf16 v[42:45], v[54:57], v[162:165], v[26:29]
	v_mfma_f32_16x16x32_bf16 v[26:29], v[58:61], v[150:153], v[98:101]
	v_mfma_f32_16x16x32_bf16 v[46:49], v[62:65], v[162:165], v[26:29]
	v_mfma_f32_16x16x32_bf16 v[26:29], v[50:53], v[170:173], v[86:89]
	v_mfma_f32_16x16x32_bf16 v[86:89], v[54:57], v[174:177], v[26:29]
	v_mfma_f32_16x16x32_bf16 v[26:29], v[58:61], v[170:173], v[82:85]
	v_mfma_f32_16x16x32_bf16 v[82:85], v[62:65], v[174:177], v[26:29]
	v_mfma_f32_16x16x32_bf16 v[26:29], v[50:53], v[178:181], v[38:41]
	v_mfma_f32_16x16x32_bf16 v[38:41], v[54:57], v[208:211], v[26:29]
	v_mfma_f32_16x16x32_bf16 v[26:29], v[58:61], v[178:181], v[34:37]
	v_mfma_f32_16x16x32_bf16 v[22:25], v[50:53], v[212:215], v[22:25]
	v_mfma_f32_16x16x32_bf16 v[18:21], v[58:61], v[212:215], v[18:21]
	v_mfma_f32_16x16x32_bf16 v[34:37], v[62:65], v[208:211], v[26:29]
	v_mfma_f32_16x16x32_bf16 v[22:25], v[54:57], v[216:219], v[22:25]
	v_mfma_f32_16x16x32_bf16 v[18:21], v[62:65], v[216:219], v[18:21]
	s_setprio 0
	s_barrier
; #define PG8_STAGE(bufoff, gbase, voff) do { _Pragma("unroll") for (int _i = 0; _i < 2; ++_i) \
;         __builtin_amdgcn_global_load_lds((const unsigned*)((const char*)(gbase) + (voff)[_i]), (PG8_LAS unsigned*)(lds + (bufoff) + ldsw + _i * 8192), 16, 0, 0); } while (0)
; #define PG8_LDA(dst, b, h) do { _Pragma("unroll") for (int m = 0; m < 4; ++m) _Pragma("unroll") for (int k = 0; k < 2; ++k) dst[m][k] = *(const PG8_LAS bf16x8*)(lds + PG8_SA(b, h) + aoff + m * 2048 + k * 1024); } while (0)
; #define PG8_LDB(dst, b, h) do { _Pragma("unroll") for (int n = 0; n < 2; ++n) _Pragma("unroll") for (int k = 0; k < 2; ++k) dst[n][k] = *(const PG8_LAS bf16x8*)(lds + PG8_SB(b, h) + boff + n * 2048 + k * 1024); } while (0)
; #define PG8_MMA(ai, bj, At, Bt) do { __builtin_amdgcn_s_setprio(1); _Pragma("unroll") for (int m = 0; m < 4; ++m) _Pragma("unroll") for (int n = 0; n < 2; ++n) _Pragma("unroll") for (int k = 0; k < 2; ++k) \
;         acc[ai][bj][m][n] = __builtin_amdgcn_mfma_f32_16x16x32_bf16(Bt[n][k], At[m][k], acc[ai][bj][m][n], 0, 0, 0); __builtin_amdgcn_s_setprio(0); } while (0)
; #define PG8_WAIT_V(n) asm volatile("s_waitcnt vmcnt(" #n ")" ::: "memory")
; template <class Epi, class Sched, bool ALIGN_EPI = false, bool SP2 = false>
; __device__ __forceinline__ void gemm_phase(PG8_LAS unsigned char* lds, const Gemm g, const Sched& S, const Epi& E) {
;     ...
;         for (int t = 0; t < ntc; t += 2) {
;             if constexpr (Epi::MID) { if (ntc == nt && t == (nt >> 1)) E.mid(acc, cur, wr, wc, fr, fq); }
;             const bool last = (t == ntc - 2);
;             const char* a1 = cA + (size_t)(t + 1) * kstep;
;             const char* a2 = last ? nA : cA + (size_t)(t + 2) * kstep; const char* b2 = last ? nB : cB + (size_t)(t + 2) * kstep;
;             const char* a3 = a2 + kstep; const char* b3 = b2 + kstep;
;             if (last && has_next) S.a_ready(nxt);
;     ...
;             PG8_LDB(B0, 1, 0); PG8_LDB(B1, 1, 1); PG8_SCHED; PG8_LDA(At, 1, 0); PG8_STAGE(PG8_SA(0, 1), a2 + hstep, voffA);
;             PG8_WAIT_V(8); PG8_WAIT_L(0); PG8_BAR; PG8_MMA(0, 0, At, B0); PG8_MMA(0, 1, At, B1); PG8_BAR; PG8_SCHED;
;             PG8_LDA(At, 1, 1); PG8_STAGE(PG8_SB(1, 0), b3, voffB); PG8_STAGE(PG8_SB(1, 1), b3 + hstep, voffB); PG8_STAGE(PG8_SA(1, 0), a3, voffA);
;             PG8_WAIT_V(8); PG8_WAIT_L(0); PG8_BAR; PG8_MMA(1, 0, At, B0); PG8_MMA(1, 1, At, B1); PG8_BAR; PG8_SCHED;
	s_add_i32 s58, 0, 0x18000
	s_add_i32 s59, 0, 0x1c000
	v_add_u32_e32 v54, s58, v1
	v_add_u32_e32 v98, s59, v1
	ds_read_b128 v[26:29], v54
	ds_read_b128 v[30:33], v54 offset:1024
	ds_read_b128 v[50:53], v54 offset:2048
	ds_read_b128 v[54:57], v54 offset:3072
	ds_read_b128 v[58:61], v98
	ds_read_b128 v[62:65], v98 offset:1024
	ds_read_b128 v[170:173], v98 offset:2048
	ds_read_b128 v[174:177], v98 offset:3072
	s_add_u32 s90, s90, 0x100000
	s_addc_u32 s91, s91, 0
	s_mov_b32 m0, s73
	ds_read_b128 v[98:101], v239 offset:32768
	ds_read_b128 v[102:105], v239 offset:33792
	ds_read_b128 v[178:181], v239 offset:34816
	ds_read_b128 v[208:211], v239 offset:35840
	ds_read_b128 v[212:215], v239 offset:36864
	ds_read_b128 v[216:219], v239 offset:37888
	ds_read_b128 v[220:223], v239 offset:38912
	ds_read_b128 v[224:227], v239 offset:39936
	global_load_lds_dwordx4 v184, s[90:91]
	s_mov_b32 m0, s75
	s_nop 0
	global_load_lds_dwordx4 v188, s[90:91]
	s_waitcnt vmcnt(8)
	s_waitcnt lgkmcnt(0)
	s_barrier
	s_setprio 1
	s_waitcnt lgkmcnt(0)
	v_mfma_f32_16x16x32_bf16 v[150:153], v[26:29], v[178:181], v[158:161]
	v_mfma_f32_16x16x32_bf16 v[6:9], v[26:29], v[98:101], v[6:9]
	v_mfma_f32_16x16x32_bf16 v[2:5], v[50:53], v[98:101], v[2:5]
	v_mfma_f32_16x16x32_bf16 v[158:161], v[30:33], v[208:211], v[150:153]
	v_mfma_f32_16x16x32_bf16 v[150:153], v[50:53], v[178:181], v[154:157]
	v_mfma_f32_16x16x32_bf16 v[142:145], v[26:29], v[212:215], v[142:145]
	v_mfma_f32_16x16x32_bf16 v[138:141], v[50:53], v[212:215], v[138:141]
	v_mfma_f32_16x16x32_bf16 v[126:129], v[26:29], v[220:223], v[126:129]
	v_mfma_f32_16x16x32_bf16 v[122:125], v[50:53], v[220:223], v[122:125]
	v_mfma_f32_16x16x32_bf16 v[6:9], v[30:33], v[102:105], v[6:9]
	v_mfma_f32_16x16x32_bf16 v[2:5], v[54:57], v[102:105], v[2:5]
	v_mfma_f32_16x16x32_bf16 v[154:157], v[54:57], v[208:211], v[150:153]
	v_mfma_f32_16x16x32_bf16 v[142:145], v[30:33], v[216:219], v[142:145]
	v_mfma_f32_16x16x32_bf16 v[138:141], v[54:57], v[216:219], v[138:141]
	v_mfma_f32_16x16x32_bf16 v[126:129], v[30:33], v[224:227], v[126:129]
	v_mfma_f32_16x16x32_bf16 v[122:125], v[54:57], v[224:227], v[122:125]
	s_setprio 0
	s_setprio 1
	v_mfma_f32_16x16x32_bf16 v[66:69], v[170:173], v[98:101], v[66:69]
	v_mfma_f32_16x16x32_bf16 v[150:153], v[58:61], v[98:101], v[166:169]
	v_mfma_f32_16x16x32_bf16 v[162:165], v[174:177], v[102:105], v[66:69]
	v_mfma_f32_16x16x32_bf16 v[66:69], v[58:61], v[178:181], v[70:73]
	v_mfma_f32_16x16x32_bf16 v[166:169], v[62:65], v[102:105], v[150:153]
	v_mfma_f32_16x16x32_bf16 v[150:153], v[62:65], v[208:211], v[66:69]
	v_mfma_f32_16x16x32_bf16 v[66:69], v[170:173], v[178:181], v[146:149]
	v_mfma_f32_16x16x32_bf16 v[146:149], v[174:177], v[208:211], v[66:69]
	v_mfma_f32_16x16x32_bf16 v[66:69], v[58:61], v[212:215], v[134:137]
	v_mfma_f32_16x16x32_bf16 v[134:137], v[62:65], v[216:219], v[66:69]
	v_mfma_f32_16x16x32_bf16 v[66:69], v[170:173], v[212:215], v[130:133]
	v_mfma_f32_16x16x32_bf16 v[130:133], v[174:177], v[216:219], v[66:69]
	v_mfma_f32_16x16x32_bf16 v[66:69], v[58:61], v[220:223], v[118:121]
	v_mfma_f32_16x16x32_bf16 v[118:121], v[62:65], v[224:227], v[66:69]
	v_mfma_f32_16x16x32_bf16 v[66:69], v[170:173], v[220:223], v[114:117]
	v_mfma_f32_16x16x32_bf16 v[114:117], v[174:177], v[224:227], v[66:69]
	s_setprio 0
	s_barrier
	s_add_i32 s58, s58, s61
	s_add_u32 s100, s88, 0x80
	s_addc_u32 s101, s89, 0
	s_mov_b32 m0, s58
	s_nop 1
	ds_read_b128 v[66:69], v239 offset:49152
	ds_read_b128 v[70:73], v239 offset:50176
	ds_read_b128 v[178:181], v239 offset:51200
	ds_read_b128 v[208:211], v239 offset:52224
	ds_read_b128 v[212:215], v239 offset:53248
	ds_read_b128 v[216:219], v239 offset:54272
	ds_read_b128 v[220:223], v239 offset:55296
	ds_read_b128 v[224:227], v239 offset:56320
	global_load_lds_dwordx4 v186, s[100:101]
	s_add_i32 m0, s58, 0x2000
	s_add_i32 s58, s59, s61
	global_load_lds_dwordx4 v190, s[100:101]
	s_add_u32 s88, s88, 0x100080
	s_addc_u32 s89, s89, 0
	s_add_u32 s100, s90, 0xfff00080
	s_addc_u32 s101, s91, -1
	s_mov_b32 m0, s58
	s_nop 0
	global_load_lds_dwordx4 v186, s[88:89]
	s_add_i32 m0, s58, 0x2000
	s_nop 0
	global_load_lds_dwordx4 v190, s[88:89]
	s_mov_b32 m0, s29
	s_nop 0
	global_load_lds_dwordx4 v184, s[100:101]
	s_mov_b32 m0, s95
	s_nop 0
	global_load_lds_dwordx4 v188, s[100:101]
	s_waitcnt vmcnt(8)
	s_waitcnt lgkmcnt(0)
	s_barrier
	s_setprio 1
	s_waitcnt lgkmcnt(0)
	v_mfma_f32_16x16x32_bf16 v[98:101], v[26:29], v[66:69], v[110:113]
	v_mfma_f32_16x16x32_bf16 v[94:97], v[26:29], v[178:181], v[94:97]
	v_mfma_f32_16x16x32_bf16 v[78:81], v[26:29], v[212:215], v[78:81]
	v_mfma_f32_16x16x32_bf16 v[10:13], v[26:29], v[220:223], v[10:13]
	v_mfma_f32_16x16x32_bf16 v[110:113], v[30:33], v[70:73], v[98:101]
	v_mfma_f32_16x16x32_bf16 v[98:101], v[50:53], v[66:69], v[106:109]
	v_mfma_f32_16x16x32_bf16 v[94:97], v[30:33], v[208:211], v[94:97]
	v_mfma_f32_16x16x32_bf16 v[90:93], v[50:53], v[178:181], v[90:93]
	v_mfma_f32_16x16x32_bf16 v[78:81], v[30:33], v[216:219], v[78:81]
	v_mfma_f32_16x16x32_bf16 v[74:77], v[50:53], v[212:215], v[74:77]
	v_mfma_f32_16x16x32_bf16 v[30:33], v[30:33], v[224:227], v[10:13]
	v_mfma_f32_16x16x32_bf16 v[10:13], v[50:53], v[220:223], v[14:17]
	v_mfma_f32_16x16x32_bf16 v[106:109], v[54:57], v[70:73], v[98:101]
	v_mfma_f32_16x16x32_bf16 v[90:93], v[54:57], v[208:211], v[90:93]
	v_mfma_f32_16x16x32_bf16 v[74:77], v[54:57], v[216:219], v[74:77]
	v_mfma_f32_16x16x32_bf16 v[26:29], v[54:57], v[224:227], v[10:13]
	s_setprio 0
	s_setprio 1
	v_mfma_f32_16x16x32_bf16 v[10:13], v[58:61], v[66:69], v[42:45]
	v_mfma_f32_16x16x32_bf16 v[102:105], v[62:65], v[70:73], v[10:13]
	v_mfma_f32_16x16x32_bf16 v[10:13], v[170:173], v[66:69], v[46:49]
	v_mfma_f32_16x16x32_bf16 v[98:101], v[174:177], v[70:73], v[10:13]
	v_mfma_f32_16x16x32_bf16 v[10:13], v[58:61], v[178:181], v[86:89]
	v_mfma_f32_16x16x32_bf16 v[86:89], v[62:65], v[208:211], v[10:13]
	v_mfma_f32_16x16x32_bf16 v[10:13], v[170:173], v[178:181], v[82:85]
	v_mfma_f32_16x16x32_bf16 v[82:85], v[174:177], v[208:211], v[10:13]
	v_mfma_f32_16x16x32_bf16 v[10:13], v[58:61], v[212:215], v[38:41]
	v_mfma_f32_16x16x32_bf16 v[38:41], v[62:65], v[216:219], v[10:13]
	v_mfma_f32_16x16x32_bf16 v[10:13], v[170:173], v[212:215], v[34:37]
	v_mfma_f32_16x16x32_bf16 v[34:37], v[174:177], v[216:219], v[10:13]
	v_mfma_f32_16x16x32_bf16 v[10:13], v[58:61], v[220:223], v[22:25]
	v_mfma_f32_16x16x32_bf16 v[22:25], v[62:65], v[224:227], v[10:13]
	v_mfma_f32_16x16x32_bf16 v[10:13], v[170:173], v[220:223], v[18:21]
	v_mfma_f32_16x16x32_bf16 v[18:21], v[174:177], v[224:227], v[10:13]
	s_setprio 0
	s_barrier
	s_add_i32 s93, s93, 2
	s_add_u32 s86, s86, 0x100
	s_addc_u32 s87, s87, 0
	s_add_u32 s85, s85, 0x100
	s_addc_u32 s92, s92, 0
	s_cmp_gt_u32 s93, 61
	s_cbranch_scc0 .LBB0_2650
	s_and_b64 vcc, exec, s[42:43]
	s_cbranch_vccz .LBB0_2653
	s_barrier
